# step12: + norm0 hoisted loads/prefetch, counter barrier for phase 1, scan loop unroll4, proj1 epilogue waits moved into gain-load path
# speedup vs baseline: 1.0158x; 1.0158x over previous
.LBB0_82:
.LBB0_83:
	s_cmp_lg_u32 s90, 0
	s_nop 0
	v_and_b32_e32 v1, 0x3ff, v0
	v_cmp_eq_u32_e32 vcc, 0, v1
	s_barrier
	s_and_saveexec_b64 s[0:1], vcc
	s_cbranch_execz .LBB0_90
	s_mov_b64 s[18:19], exec
	buffer_wbl2 sc1
	s_waitcnt vmcnt(0)
	s_waitcnt vmcnt(0)
	v_mbcnt_lo_u32_b32 v2, s18, 0
	s_add_u32 s6, s86, 0x3b79d000
	v_mbcnt_hi_u32_b32 v2, s19, v2
	s_addc_u32 s7, s87, 0
	v_cmp_eq_u32_e32 vcc, 0, v2
	s_and_saveexec_b64 s[20:21], vcc
	s_cbranch_execz .LBB0_87
	s_bcnt1_i32_b64 s3, s[18:19]
	v_mov_b32_e32 v2, 0
	v_mov_b32_e32 v3, s3
	global_atomic_add v2, v3, s[6:7]
.LBB0_87:
	s_or_b64 exec, exec, s[20:21]
	s_sub_i32 s3, 1, s90
	s_mul_i32 s3, s33, s3
	v_mov_b32_e32 v2, 0
.LBB0_88:
	global_load_dword v3, v2, s[6:7] sc1
	s_waitcnt vmcnt(0)
	v_cmp_gt_u32_e32 vcc, s3, v3
	s_cbranch_vccnz .LBB0_88
	buffer_inv sc1
	s_waitcnt vmcnt(0)

.LBB0_103:
	v_lshrrev_b32_e32 v2, 6, v1
	v_lshl_add_u32 v22, s2, 3, v2
	s_mov_b32 s0, 0x8200
	v_cmp_gt_i32_e32 vcc, s0, v22
	s_and_saveexec_b64 s[6:7], vcc
	s_cbranch_execz .LBB0_122
	v_lshlrev_b32_e32 v1, 2, v1
	v_and_b32_e32 v4, 0xfc, v1
	v_mbcnt_lo_u32_b32 v1, -1, 0
	v_mbcnt_hi_u32_b32 v3, -1, v1
	v_and_b32_e32 v1, 64, v3
	v_add_u32_e32 v5, 64, v1
	v_xor_b32_e32 v1, 32, v3
	v_cmp_lt_i32_e32 vcc, v1, v5
	v_xor_b32_e32 v6, 16, v3
	s_add_u32 s0, s86, 0x3b700000
	v_cndmask_b32_e32 v1, v3, v1, vcc
	v_cmp_lt_i32_e32 vcc, v6, v5
	v_mov_b32_e32 v25, 0
	v_lshlrev_b32_e32 v24, 2, v4
	v_cndmask_b32_e32 v6, v3, v6, vcc
	v_lshlrev_b32_e32 v48, 2, v6
	v_xor_b32_e32 v6, 8, v3
	v_cmp_lt_i32_e32 vcc, v6, v5
	s_addc_u32 s1, s87, 0
	s_lshl_b32 s3, s33, 3
	v_cndmask_b32_e32 v6, v3, v6, vcc
	v_lshlrev_b32_e32 v49, 2, v6
	v_xor_b32_e32 v6, 4, v3
	v_cmp_lt_i32_e32 vcc, v6, v5
	v_lshl_add_u64 v[26:27], s[52:53], 0, v[24:25]
	v_lshlrev_b32_e32 v24, 1, v4
	v_cndmask_b32_e32 v6, v3, v6, vcc
	v_lshlrev_b32_e32 v50, 2, v6
	v_xor_b32_e32 v6, 2, v3
	v_cmp_lt_i32_e32 vcc, v6, v5
	v_or_b32_e32 v8, 0x200, v4
	v_or_b32_e32 v10, 0x300, v4
	v_cndmask_b32_e32 v6, v3, v6, vcc
	v_lshlrev_b32_e32 v51, 2, v6
	v_xor_b32_e32 v6, 1, v3
	v_cmp_lt_i32_e32 vcc, v6, v5
	s_add_u32 s18, s84, 0x28600000
	v_lshl_add_u64 v[12:13], s[86:87], 0, v[24:25]
	v_cndmask_b32_e32 v3, v3, v6, vcc
	v_or_b32_e32 v6, 0x100, v4
	s_mov_b64 s[20:21], 0x30c00000
	v_lshlrev_b32_e32 v2, 5, v2
	v_lshlrev_b32_e32 v1, 2, v1
	v_lshlrev_b32_e32 v52, 2, v3
	s_addc_u32 s19, s85, 0
	v_lshl_add_u64 v[28:29], v[12:13], 0, s[20:21]
	v_lshl_add_u32 v53, s2, 8, v2
	s_lshl_b32 s30, s33, 8
	s_mov_b64 s[20:21], 0
	s_mov_b32 s31, 0x8000
	s_movk_i32 s34, 0x7fff
	v_lshlrev_b32_e32 v30, 2, v4
	v_mov_b32_e32 v31, v25
	s_mov_b64 s[22:23], 0x29208000
	s_movk_i32 s35, 0x3000
	v_mov_b64_e32 v[32:33], s[0:1]
	v_mov_b32_e32 v54, 0x358637bd
	s_mov_b32 s40, 0x800000
	s_movk_i32 s41, 0xfff
	s_mov_b64 s[24:25], 0x1000
	v_lshlrev_b32_e32 v34, 2, v6
	v_mov_b32_e32 v35, v25
	v_lshlrev_b32_e32 v36, 2, v8
	v_mov_b32_e32 v37, v25
	v_lshlrev_b32_e32 v38, 2, v10
	v_mov_b32_e32 v39, v25
	s_mov_b32 s44, 0x81ff
	global_load_dwordx4 v[106:109], v[26:27], off
	global_load_dwordx4 v[110:113], v[26:27], off offset:1024
	global_load_dwordx4 v[114:117], v[26:27], off offset:2048
	global_load_dwordx4 v[118:121], v[26:27], off offset:3072
	v_mov_b32_e32 v140, s8
	v_mov_b32_e32 v141, s9
	v_mov_b32_e32 v142, s10
	v_mov_b32_e32 v143, s11
	v_add_u32_e32 v138, 0xffff8000, v22
	v_cmp_lt_i32_e64 s[26:27], s34, v22
	v_mov_b32_e32 v139, 0
	s_nop 0
	v_cndmask_b32_e64 v138, v22, v138, s[26:27]
	v_cndmask_b32_e64 v144, v140, v142, s[26:27]
	v_cndmask_b32_e64 v145, v141, v143, s[26:27]
	v_lshlrev_b64 v[138:139], 12, v[138:139]
	v_lshl_add_u64 v[138:139], v[144:145], 0, v[138:139]
	v_lshl_add_u64 v[138:139], v[138:139], 0, v[30:31]
	global_load_dwordx4 v[134:137], v[138:139], off
	global_load_dwordx4 v[130:133], v[138:139], off offset:1024
	global_load_dwordx4 v[126:129], v[138:139], off offset:2048
	global_load_dwordx4 v[122:125], v[138:139], off offset:3072
	s_waitcnt vmcnt(0)
	s_branch .LBB0_106

.LBB0_106:
	v_cmp_gt_i32_e32 vcc, s31, v22
	v_cmp_lt_i32_e64 s[0:1], s34, v22
	v_add_u32_e32 v24, 0xffff8000, v22
	v_ashrrev_i32_e32 v23, 31, v22
	s_waitcnt vmcnt(4)
	v_mov_b32_e32 v2, v122
	v_mov_b32_e32 v3, v123
	v_mov_b32_e32 v4, v124
	v_mov_b32_e32 v5, v125
	v_mov_b32_e32 v6, v126
	v_mov_b32_e32 v7, v127
	v_mov_b32_e32 v8, v128
	v_mov_b32_e32 v9, v129
	v_mov_b32_e32 v10, v130
	v_mov_b32_e32 v11, v131
	v_mov_b32_e32 v12, v132
	v_mov_b32_e32 v13, v133
	v_mov_b32_e32 v14, v134
	v_mov_b32_e32 v15, v135
	v_mov_b32_e32 v16, v136
	v_mov_b32_e32 v17, v137
	s_and_saveexec_b64 s[26:27], s[0:1]
	s_xor_b64 s[0:1], exec, s[26:27]
	v_and_b32_e32 v18, 0x7ffffc00, v53
	v_mov_b32_e32 v19, v25
	v_lshl_add_u64 v[18:19], v[18:19], 2, s[84:85]
	v_lshl_add_u64 v[46:47], v[18:19], 0, s[22:23]
	s_andn2_saveexec_b64 s[0:1], s[0:1]
	v_ashrrev_i32_e32 v18, 2, v22
	v_and_b32_e32 v18, 0xfffffc00, v18
	v_ashrrev_i32_e32 v19, 31, v18
	v_lshl_add_u64 v[46:47], v[18:19], 2, s[18:19]
	s_or_b64 exec, exec, s[0:1]
	v_lshrrev_b32_e32 v19, 5, v24
	v_ashrrev_i32_e32 v18, 12, v22
	v_add_u32_e32 v19, 8, v19
	v_cndmask_b32_e32 v18, v19, v18, vcc
	v_mad_i64_i32 v[18:19], s[0:1], v18, s35, v[32:33]
	v_lshl_add_u64 v[40:41], v[18:19], 0, s[24:25]
	v_lshl_add_u64 v[44:45], v[18:19], 0, v[30:31]
	v_lshl_add_u64 v[66:67], v[40:41], 0, v[30:31]
	v_lshl_add_u64 v[68:69], v[40:41], 0, v[34:35]
	v_lshl_add_u64 v[70:71], v[40:41], 0, v[36:37]
	v_lshl_add_u64 v[72:73], v[40:41], 0, v[38:39]
	global_load_dwordx4 v[74:77], v[66:67], off
	global_load_dwordx4 v[90:93], v[44:45], off
	global_load_dwordx4 v[78:81], v[68:69], off
	global_load_dwordx4 v[94:97], v[44:45], off offset:1024
	global_load_dwordx4 v[82:85], v[70:71], off
	global_load_dwordx4 v[98:101], v[44:45], off offset:2048
	global_load_dwordx4 v[86:89], v[72:73], off
	global_load_dwordx4 v[102:105], v[44:45], off offset:3072
	v_add_u32_e32 v146, s3, v22
	v_min_i32_e32 v146, s44, v146
	v_add_u32_e32 v138, 0xffff8000, v146
	v_cmp_lt_i32_e64 s[26:27], s34, v146
	v_mov_b32_e32 v139, 0
	s_nop 0
	v_cndmask_b32_e64 v138, v146, v138, s[26:27]
	v_cndmask_b32_e64 v144, v140, v142, s[26:27]
	v_cndmask_b32_e64 v145, v141, v143, s[26:27]
	v_lshlrev_b64 v[138:139], 12, v[138:139]
	v_lshl_add_u64 v[138:139], v[144:145], 0, v[138:139]
	v_lshl_add_u64 v[138:139], v[138:139], 0, v[30:31]
	global_load_dwordx4 v[134:137], v[138:139], off
	global_load_dwordx4 v[130:133], v[138:139], off offset:1024
	global_load_dwordx4 v[126:129], v[138:139], off offset:2048
	global_load_dwordx4 v[122:125], v[138:139], off offset:3072
	v_mul_f32_e32 v18, v15, v15
	v_mul_f32_e32 v19, v11, v11
	v_mul_f32_e32 v20, v7, v7
	v_fmac_f32_e32 v18, v14, v14
	v_fmac_f32_e32 v19, v10, v10
	v_mul_f32_e32 v21, v3, v3
	v_fmac_f32_e32 v20, v6, v6
	v_fmac_f32_e32 v18, v16, v16
	v_fmac_f32_e32 v19, v12, v12
	v_fmac_f32_e32 v21, v2, v2
	v_fmac_f32_e32 v20, v8, v8
	v_fmac_f32_e32 v18, v17, v17
	v_fmac_f32_e32 v19, v13, v13
	v_fmac_f32_e32 v21, v4, v4
	v_fmac_f32_e32 v20, v9, v9
	v_add_f32_e32 v18, v18, v19
	v_add_f32_e32 v18, v18, v20
	v_fmac_f32_e32 v21, v5, v5
	v_add_f32_e32 v18, v18, v21
	ds_bpermute_b32 v19, v1, v18
	s_waitcnt lgkmcnt(0)
	v_add_f32_e32 v18, v18, v19
	ds_bpermute_b32 v19, v48, v18
	s_waitcnt lgkmcnt(0)
	v_add_f32_e32 v18, v18, v19
	ds_bpermute_b32 v19, v49, v18
	s_waitcnt lgkmcnt(0)
	v_add_f32_e32 v18, v18, v19
	ds_bpermute_b32 v19, v50, v18
	s_waitcnt lgkmcnt(0)
	v_add_f32_e32 v18, v18, v19
	ds_bpermute_b32 v19, v51, v18
	s_waitcnt lgkmcnt(0)
	v_add_f32_e32 v42, v18, v19
	ds_bpermute_b32 v43, v52, v42
	v_and_b32_e32 v55, 0xfff, v22
	s_waitcnt lgkmcnt(0)
	v_add_f32_e32 v24, v42, v43
	v_and_b32_e32 v64, 31, v22
	v_cmp_eq_u32_e64 s[0:1], s41, v55
	v_lshlrev_b64 v[42:43], 11, v[22:23]
	v_fmamk_f32 v23, v24, 0x3a800000, v54
	v_cndmask_b32_e64 v24, 0, 1, s[0:1]
	v_cmp_eq_u32_e64 s[0:1], 31, v64
	v_mul_f32_e32 v64, 0x4b800000, v23
	v_lshl_add_u64 v[42:43], v[28:29], 0, v[42:43]
	v_cndmask_b32_e64 v55, 0, 1, s[0:1]
	v_cmp_gt_f32_e64 s[0:1], s40, v23
	v_cndmask_b32_e32 v24, v55, v24, vcc
	v_and_b32_e32 v24, 1, v24
	v_cndmask_b32_e64 v23, v23, v64, s[0:1]
	v_rsq_f32_e32 v23, v23
	v_cmp_eq_u32_e32 vcc, 1, v24
	v_lshl_add_u64 v[46:47], v[46:47], 0, v[30:31]
	v_mul_f32_e32 v24, 0x45800000, v23
	v_cndmask_b32_e64 v23, v23, v24, s[0:1]
	s_waitcnt vmcnt(4)
	v_mul_f32_e32 v14, v14, v23
	v_mul_f32_e32 v15, v15, v23
	v_mul_f32_e32 v16, v16, v23
	v_mul_f32_e32 v17, v17, v23
	v_mul_f32_e32 v14, v14, v106
	v_mul_f32_e32 v15, v15, v107
	v_mul_f32_e32 v16, v16, v108
	v_mul_f32_e32 v17, v17, v109
	v_add_f32_e32 v56, 1.0, v74
	v_add_f32_e32 v57, 1.0, v75
	v_add_f32_e32 v58, 1.0, v76
	v_add_f32_e32 v59, 1.0, v77
	v_fma_f32 v90, v14, v56, v90
	v_fma_f32 v91, v15, v57, v91
	v_fma_f32 v92, v16, v58, v92
	v_fmac_f32_e32 v93, v17, v59
	v_cvt_pk_bf16_f32 v60, v90, v91
	v_cvt_pk_bf16_f32 v61, v92, v93
	global_store_dwordx2 v[42:43], v[60:61], off
	s_and_saveexec_b64 s[0:1], vcc
	s_cbranch_execz .Lnorm0_skip0
	global_store_dwordx4 v[46:47], v[90:93], off
.Lnorm0_skip0:
	s_or_b64 exec, exec, s[0:1]
	v_mul_f32_e32 v10, v10, v23
	v_mul_f32_e32 v11, v11, v23
	v_mul_f32_e32 v12, v12, v23
	v_mul_f32_e32 v13, v13, v23
	v_mul_f32_e32 v10, v10, v110
	v_mul_f32_e32 v11, v11, v111
	v_mul_f32_e32 v12, v12, v112
	v_mul_f32_e32 v13, v13, v113
	v_add_f32_e32 v56, 1.0, v78
	v_add_f32_e32 v57, 1.0, v79
	v_add_f32_e32 v58, 1.0, v80
	v_add_f32_e32 v59, 1.0, v81
	v_fma_f32 v94, v10, v56, v94
	v_fma_f32 v95, v11, v57, v95
	v_fma_f32 v96, v12, v58, v96
	v_fmac_f32_e32 v97, v13, v59
	v_cvt_pk_bf16_f32 v60, v94, v95
	v_cvt_pk_bf16_f32 v61, v96, v97
	global_store_dwordx2 v[42:43], v[60:61], off offset:512
	s_and_saveexec_b64 s[0:1], vcc
	s_cbranch_execz .Lnorm0_skip1
	global_store_dwordx4 v[46:47], v[94:97], off offset:1024
.Lnorm0_skip1:
	s_or_b64 exec, exec, s[0:1]
	v_mul_f32_e32 v6, v6, v23
	v_mul_f32_e32 v7, v7, v23
	v_mul_f32_e32 v8, v8, v23
	v_mul_f32_e32 v9, v9, v23
	v_mul_f32_e32 v6, v6, v114
	v_mul_f32_e32 v7, v7, v115
	v_mul_f32_e32 v8, v8, v116
	v_mul_f32_e32 v9, v9, v117
	v_add_f32_e32 v56, 1.0, v82
	v_add_f32_e32 v57, 1.0, v83
	v_add_f32_e32 v58, 1.0, v84
	v_add_f32_e32 v59, 1.0, v85
	v_fma_f32 v98, v6, v56, v98
	v_fma_f32 v99, v7, v57, v99
	v_fma_f32 v100, v8, v58, v100
	v_fmac_f32_e32 v101, v9, v59
	v_cvt_pk_bf16_f32 v60, v98, v99
	v_cvt_pk_bf16_f32 v61, v100, v101
	global_store_dwordx2 v[42:43], v[60:61], off offset:1024
	s_and_saveexec_b64 s[0:1], vcc
	s_cbranch_execz .Lnorm0_skip2
	global_store_dwordx4 v[46:47], v[98:101], off offset:2048
.Lnorm0_skip2:
	s_or_b64 exec, exec, s[0:1]
	v_mul_f32_e32 v2, v2, v23
	v_mul_f32_e32 v3, v3, v23
	v_mul_f32_e32 v4, v4, v23
	v_mul_f32_e32 v5, v5, v23
	v_mul_f32_e32 v2, v2, v118
	v_mul_f32_e32 v3, v3, v119
	v_mul_f32_e32 v4, v4, v120
	v_mul_f32_e32 v5, v5, v121
	v_add_f32_e32 v56, 1.0, v86
	v_add_f32_e32 v57, 1.0, v87
	v_add_f32_e32 v58, 1.0, v88
	v_add_f32_e32 v59, 1.0, v89
	v_fma_f32 v102, v2, v56, v102
	v_fma_f32 v103, v3, v57, v103
	v_fma_f32 v104, v4, v58, v104
	v_fmac_f32_e32 v105, v5, v59
	v_cvt_pk_bf16_f32 v60, v102, v103
	v_cvt_pk_bf16_f32 v61, v104, v105
	global_store_dwordx2 v[42:43], v[60:61], off offset:1536
	s_and_saveexec_b64 s[0:1], vcc
	s_cbranch_execz .LBB0_105
	global_store_dwordx4 v[46:47], v[102:105], off offset:3072
	s_branch .LBB0_105
.LBB0_122:
	s_or_b64 exec, exec, s[6:7]
	s_waitcnt vmcnt(0)
.LBB0_123:
	s_cmp_gt_i32 s90, 2
	s_cselect_b64 s[18:19], -1, 0
	s_cmp_lt_i32 s91, 3
	s_cselect_b64 s[0:1], -1, 0
	s_or_b64 s[0:1], s[18:19], s[0:1]
	s_and_b64 vcc, exec, s[0:1]
	s_cbranch_vccnz .LBB0_497
	s_andn2_b64 vcc, exec, s[4:5]
	s_cbranch_vccnz .LBB0_126
	v_and_b32_e32 v1, 0x3ff, v0
	s_cbranch_execz .LBB0_127
	s_branch .LBB0_147

.LBB0_131:
	s_or_b64 exec, exec, s[20:21]
	s_sub_i32 s3, 2, s90
	s_mul_i32 s3, s33, s3
	v_mov_b32_e32 v2, 0

.LBB0_505:
	s_or_b64 exec, exec, s[20:21]
	s_sub_i32 s3, 3, s90
	s_mul_i32 s3, s33, s3
	v_mov_b32_e32 v1, 0

.LBB0_544:
	s_lshl_b32 s57, s57, 6
	s_sub_i32 s50, s30, s57
	s_cmp_lt_i32 s50, 1
	s_cbranch_scc1 .LBB0_551
	ds_read_b128 v[142:145], v185
	ds_read_b128 v[138:141], v185 offset:32768
	ds_read_b128 v[126:129], v185 offset:24576
	ds_read_b32 v170, v183 offset:40960
	ds_read_b128 v[134:137], v185 offset:8192
	ds_read_b128 v[130:133], v185 offset:16384
	ds_read_b128 v[162:165], v193
	ds_read_b128 v[158:161], v193 offset:32768
	ds_read_b128 v[154:157], v193 offset:24576
	ds_read_b32 v206, v192
	ds_read_b128 v[146:149], v193 offset:8192
	ds_read_b128 v[150:153], v193 offset:16384
	s_min_i32 s59, s50, 64
	s_mov_b32 s60, 0
	v_add_u32_e32 v203, 0x100, v185
	v_add_u32_e32 v204, 0x100, v192
	v_lshrrev_b32_e32 v222, 1, v185
	v_mov_b32_e32 v221, 0x800
	v_lshl_add_u32 v222, v183, 4, v222
	v_add_u32_e32 v222, 0x20000, v222
	v_cndmask_b32_e64 v220, 0, v221, s[0:1]
	v_cndmask_b32_e64 v205, v222, v191, s[0:1]
	s_waitcnt lgkmcnt(6)
.Lscan_seq:
	s_waitcnt lgkmcnt(11)
	v_dot2_f32_f16 v215, v202, v142, 0
	v_dot2_f32_f16 v214, v202, v138, 0
	v_dot2_f32_f16 v215, v175, v143, v215
	v_dot2_f32_f16 v214, v175, v139, v214
	v_dot2_f32_f16 v215, v201, v144, v215
	v_dot2_f32_f16 v214, v201, v140, v214
	v_dot2_f32_f16 v215, v200, v145, v215
	v_dot2_f32_f16 v214, v200, v141, v214
	ds_read_b128 v[142:145], v203
	ds_read_b128 v[138:141], v203 offset:32768
	v_add_f32_dpp v215, v215, v215 quad_perm:[1,0,3,2] row_mask:0xf bank_mask:0xf bound_ctrl:1
	v_add_f32_dpp v214, v214, v214 quad_perm:[1,0,3,2] row_mask:0xf bank_mask:0xf bound_ctrl:1
	s_waitcnt lgkmcnt(9)
	v_pk_mul_f16 v126, v170, v126
	v_pk_mul_f16 v127, v170, v127
	v_add_f32_dpp v215, v215, v215 quad_perm:[2,3,0,1] row_mask:0xf bank_mask:0xf bound_ctrl:1
	v_add_f32_dpp v214, v214, v214 quad_perm:[2,3,0,1] row_mask:0xf bank_mask:0xf bound_ctrl:1
	v_pk_mul_f16 v128, v170, v128
	v_pk_mul_f16 v129, v170, v129
	v_add_f32_dpp v215, v215, v215 row_half_mirror row_mask:0xf bank_mask:0xf bound_ctrl:1
	v_add_f32_dpp v214, v214, v214 row_half_mirror row_mask:0xf bank_mask:0xf bound_ctrl:1
	v_cvt_pk_f16_f32 v218, v215, v215
	ds_write_b64 v205, v[214:215]
	v_pk_fma_f16 v126, v218, v130, v126 neg_lo:[1,0,0] neg_hi:[1,0,0]
	v_pk_fma_f16 v127, v218, v131, v127 neg_lo:[1,0,0] neg_hi:[1,0,0]
	v_pk_fma_f16 v128, v218, v132, v128 neg_lo:[1,0,0] neg_hi:[1,0,0]
	v_pk_fma_f16 v129, v218, v133, v129 neg_lo:[1,0,0] neg_hi:[1,0,0]
	v_pk_fma_f16 v202, v202, v134, v126
	v_pk_fma_f16 v175, v175, v135, v127
	v_pk_fma_f16 v201, v201, v136, v128
	v_pk_fma_f16 v200, v200, v137, v129
	ds_read_b128 v[126:129], v203 offset:24576
	ds_read_b32 v170, v204
	ds_read_b128 v[134:137], v203 offset:8192
	ds_read_b128 v[130:133], v203 offset:16384
	s_waitcnt lgkmcnt(11)
	v_dot2_f32_f16 v217, v202, v162, 0
	v_dot2_f32_f16 v216, v202, v158, 0
	v_dot2_f32_f16 v217, v175, v163, v217
	v_dot2_f32_f16 v216, v175, v159, v216
	v_dot2_f32_f16 v217, v201, v164, v217
	v_dot2_f32_f16 v216, v201, v160, v216
	v_dot2_f32_f16 v217, v200, v165, v217
	v_dot2_f32_f16 v216, v200, v161, v216
	ds_read_b128 v[162:165], v203 offset:128
	ds_read_b128 v[158:161], v203 offset:32896
	v_add_f32_dpp v217, v217, v217 quad_perm:[1,0,3,2] row_mask:0xf bank_mask:0xf bound_ctrl:1
	v_add_f32_dpp v216, v216, v216 quad_perm:[1,0,3,2] row_mask:0xf bank_mask:0xf bound_ctrl:1
	s_waitcnt lgkmcnt(9)
	v_pk_mul_f16 v154, v206, v154
	v_pk_mul_f16 v155, v206, v155
	v_add_f32_dpp v217, v217, v217 quad_perm:[2,3,0,1] row_mask:0xf bank_mask:0xf bound_ctrl:1
	v_add_f32_dpp v216, v216, v216 quad_perm:[2,3,0,1] row_mask:0xf bank_mask:0xf bound_ctrl:1
	v_pk_mul_f16 v156, v206, v156
	v_pk_mul_f16 v157, v206, v157
	v_add_f32_dpp v217, v217, v217 row_half_mirror row_mask:0xf bank_mask:0xf bound_ctrl:1
	v_add_f32_dpp v216, v216, v216 row_half_mirror row_mask:0xf bank_mask:0xf bound_ctrl:1
	v_cvt_pk_f16_f32 v219, v217, v217
	ds_write_b64 v205, v[216:217] offset:512
	v_pk_fma_f16 v154, v219, v150, v154 neg_lo:[1,0,0] neg_hi:[1,0,0]
	v_pk_fma_f16 v155, v219, v151, v155 neg_lo:[1,0,0] neg_hi:[1,0,0]
	v_pk_fma_f16 v156, v219, v152, v156 neg_lo:[1,0,0] neg_hi:[1,0,0]
	v_pk_fma_f16 v157, v219, v153, v157 neg_lo:[1,0,0] neg_hi:[1,0,0]
	v_pk_fma_f16 v202, v202, v146, v154
	v_pk_fma_f16 v175, v175, v147, v155
	v_pk_fma_f16 v201, v201, v148, v156
	v_pk_fma_f16 v200, v200, v149, v157
	ds_read_b128 v[154:157], v203 offset:24704
	ds_read_b32 v206, v204 offset:256
	ds_read_b128 v[146:149], v203 offset:8320
	ds_read_b128 v[150:153], v203 offset:16512
	s_waitcnt lgkmcnt(11)
	v_dot2_f32_f16 v215, v202, v142, 0
	v_dot2_f32_f16 v214, v202, v138, 0
	v_dot2_f32_f16 v215, v175, v143, v215
	v_dot2_f32_f16 v214, v175, v139, v214
	v_dot2_f32_f16 v215, v201, v144, v215
	v_dot2_f32_f16 v214, v201, v140, v214
	v_dot2_f32_f16 v215, v200, v145, v215
	v_dot2_f32_f16 v214, v200, v141, v214
	ds_read_b128 v[142:145], v203 offset:256
	ds_read_b128 v[138:141], v203 offset:33024
	v_add_f32_dpp v215, v215, v215 quad_perm:[1,0,3,2] row_mask:0xf bank_mask:0xf bound_ctrl:1
	v_add_f32_dpp v214, v214, v214 quad_perm:[1,0,3,2] row_mask:0xf bank_mask:0xf bound_ctrl:1
	s_waitcnt lgkmcnt(9)
	v_pk_mul_f16 v126, v170, v126
	v_pk_mul_f16 v127, v170, v127
	v_add_f32_dpp v215, v215, v215 quad_perm:[2,3,0,1] row_mask:0xf bank_mask:0xf bound_ctrl:1
	v_add_f32_dpp v214, v214, v214 quad_perm:[2,3,0,1] row_mask:0xf bank_mask:0xf bound_ctrl:1
	v_pk_mul_f16 v128, v170, v128
	v_pk_mul_f16 v129, v170, v129
	v_add_f32_dpp v215, v215, v215 row_half_mirror row_mask:0xf bank_mask:0xf bound_ctrl:1
	v_add_f32_dpp v214, v214, v214 row_half_mirror row_mask:0xf bank_mask:0xf bound_ctrl:1
	v_cvt_pk_f16_f32 v218, v215, v215
	ds_write_b64 v205, v[214:215] offset:1024
	v_pk_fma_f16 v126, v218, v130, v126 neg_lo:[1,0,0] neg_hi:[1,0,0]
	v_pk_fma_f16 v127, v218, v131, v127 neg_lo:[1,0,0] neg_hi:[1,0,0]
	v_pk_fma_f16 v128, v218, v132, v128 neg_lo:[1,0,0] neg_hi:[1,0,0]
	v_pk_fma_f16 v129, v218, v133, v129 neg_lo:[1,0,0] neg_hi:[1,0,0]
	v_pk_fma_f16 v202, v202, v134, v126
	v_pk_fma_f16 v175, v175, v135, v127
	v_pk_fma_f16 v201, v201, v136, v128
	v_pk_fma_f16 v200, v200, v137, v129
	ds_read_b128 v[126:129], v203 offset:24832
	ds_read_b32 v170, v204 offset:512
	ds_read_b128 v[134:137], v203 offset:8448
	ds_read_b128 v[130:133], v203 offset:16640
	s_waitcnt lgkmcnt(11)
	v_dot2_f32_f16 v217, v202, v162, 0
	v_dot2_f32_f16 v216, v202, v158, 0
	v_dot2_f32_f16 v217, v175, v163, v217
	v_dot2_f32_f16 v216, v175, v159, v216
	v_dot2_f32_f16 v217, v201, v164, v217
	v_dot2_f32_f16 v216, v201, v160, v216
	v_dot2_f32_f16 v217, v200, v165, v217
	v_dot2_f32_f16 v216, v200, v161, v216
	ds_read_b128 v[162:165], v203 offset:384
	ds_read_b128 v[158:161], v203 offset:33152
	v_add_f32_dpp v217, v217, v217 quad_perm:[1,0,3,2] row_mask:0xf bank_mask:0xf bound_ctrl:1
	v_add_f32_dpp v216, v216, v216 quad_perm:[1,0,3,2] row_mask:0xf bank_mask:0xf bound_ctrl:1
	s_waitcnt lgkmcnt(9)
	v_pk_mul_f16 v154, v206, v154
	v_pk_mul_f16 v155, v206, v155
	v_add_f32_dpp v217, v217, v217 quad_perm:[2,3,0,1] row_mask:0xf bank_mask:0xf bound_ctrl:1
	v_add_f32_dpp v216, v216, v216 quad_perm:[2,3,0,1] row_mask:0xf bank_mask:0xf bound_ctrl:1
	v_pk_mul_f16 v156, v206, v156
	v_pk_mul_f16 v157, v206, v157
	v_add_f32_dpp v217, v217, v217 row_half_mirror row_mask:0xf bank_mask:0xf bound_ctrl:1
	v_add_f32_dpp v216, v216, v216 row_half_mirror row_mask:0xf bank_mask:0xf bound_ctrl:1
	v_cvt_pk_f16_f32 v219, v217, v217
	ds_write_b64 v205, v[216:217] offset:1536
	v_pk_fma_f16 v154, v219, v150, v154 neg_lo:[1,0,0] neg_hi:[1,0,0]
	v_pk_fma_f16 v155, v219, v151, v155 neg_lo:[1,0,0] neg_hi:[1,0,0]
	v_pk_fma_f16 v156, v219, v152, v156 neg_lo:[1,0,0] neg_hi:[1,0,0]
	v_pk_fma_f16 v157, v219, v153, v157 neg_lo:[1,0,0] neg_hi:[1,0,0]
	v_pk_fma_f16 v202, v202, v146, v154
	v_pk_fma_f16 v175, v175, v147, v155
	v_pk_fma_f16 v201, v201, v148, v156
	v_pk_fma_f16 v200, v200, v149, v157
	ds_read_b128 v[154:157], v203 offset:24960
	ds_read_b32 v206, v204 offset:768
	ds_read_b128 v[146:149], v203 offset:8576
	ds_read_b128 v[150:153], v203 offset:16768
	v_add_u32_e32 v203, 0x200, v203
	v_add_u32_e32 v204, 0x400, v204
	v_add_u32_e32 v205, v220, v205
	s_add_i32 s60, s60, 4
	s_cmp_lt_i32 s60, s59
	s_cbranch_scc1 .Lscan_seq

.LBB0_565:
	s_or_b64 exec, exec, s[18:19]
	s_sub_i32 s3, 4, s90
	s_mul_i32 s3, s33, s3
	v_mov_b32_e32 v1, 0

.LBB0_623:
	s_or_b64 exec, exec, s[10:11]
	s_sub_i32 s3, 5, s90
	s_mul_i32 s3, s33, s3
	v_mov_b32_e32 v2, 0

.LBB0_646:
.LBB0_647:
	s_cmp_lg_u32 s90, 5
	s_cbranch_scc0 .LBB0_655
	v_and_b32_e32 v2, 0x3ff, v0
	v_cmp_eq_u32_e32 vcc, 0, v2
	s_barrier
	s_and_saveexec_b64 s[0:1], vcc
	s_cbranch_execz .LBB0_654
	s_mov_b64 s[6:7], exec
	buffer_wbl2 sc1
	s_waitcnt vmcnt(0)
	s_waitcnt vmcnt(0)
	v_mbcnt_lo_u32_b32 v1, s6, 0
	s_add_u32 s4, s86, 0x3b79d000
	v_mbcnt_hi_u32_b32 v1, s7, v1
	s_addc_u32 s5, s87, 0
	v_cmp_eq_u32_e32 vcc, 0, v1
	s_and_saveexec_b64 s[8:9], vcc
	s_cbranch_execz .LBB0_651
	s_bcnt1_i32_b64 s3, s[6:7]
	v_mov_b32_e32 v1, 0
	v_mov_b32_e32 v3, s3
	global_atomic_add v1, v3, s[4:5]
.LBB0_651:
	s_or_b64 exec, exec, s[8:9]
	s_sub_i32 s3, 6, s90
	s_mul_i32 s3, s33, s3
	v_mov_b32_e32 v1, 0
.LBB0_652:
	global_load_dword v3, v1, s[4:5] sc1
	s_waitcnt vmcnt(0)
	v_cmp_gt_u32_e32 vcc, s3, v3
	s_cbranch_vccnz .LBB0_652
	buffer_inv sc1
	s_waitcnt vmcnt(0)

.LBB0_816:
	ds_read_b128 v[138:141], v136
	ds_read_b128 v[142:145], v135
	ds_read_b128 v[218:221], v135 offset:16896
	ds_read_b128 v[222:225], v137
	v_add_u32_e32 v226, s6, v134
	v_add_u32_e32 v228, s6, v133
	v_add_u32_e32 v230, s6, v132
	v_ashrrev_i32_e32 v227, 31, v226
	v_add_u32_e32 v232, 32, v226
	s_add_i32 s6, s6, 64
	v_ashrrev_i32_e32 v229, 31, v228
	v_ashrrev_i32_e32 v231, 31, v230
	v_lshlrev_b64 v[226:227], 12, v[226:227]
	v_ashrrev_i32_e32 v233, 31, v232
	v_add_u32_e32 v137, 0x8400, v137
	v_add_u32_e32 v136, 0x8400, v136
	v_add_u32_e32 v135, 0x8400, v135
	s_cmpk_eq_i32 s6, 0x100
	v_lshlrev_b64 v[228:229], 12, v[228:229]
	v_lshlrev_b64 v[230:231], 12, v[230:231]
	v_lshl_add_u64 v[226:227], v[130:131], 0, v[226:227]
	v_lshlrev_b64 v[232:233], 12, v[232:233]
	v_lshl_add_u64 v[228:229], v[130:131], 0, v[228:229]
	v_lshl_add_u64 v[230:231], v[130:131], 0, v[230:231]
	v_lshl_add_u64 v[232:233], v[130:131], 0, v[232:233]
	s_waitcnt lgkmcnt(2)
	global_store_dwordx4 v[226:227], v[142:145], off
	global_store_dwordx4 v[228:229], v[138:141], off
	s_waitcnt lgkmcnt(1)
	global_store_dwordx4 v[232:233], v[218:221], off
	s_waitcnt lgkmcnt(0)
	global_store_dwordx4 v[230:231], v[222:225], off
	s_cbranch_scc0 .LBB0_816
	s_and_b64 vcc, exec, s[34:35]
	s_barrier
	s_cbranch_vccz .LBB0_955
	v_cndmask_b32_e64 v130, 0, 1, s[38:39]
	v_cmp_ne_u32_e64 s[6:7], 1, v130
	s_and_saveexec_b64 s[42:43], s[8:9]
	s_cbranch_execz .LBB0_884
	v_mov_b32_e32 v133, 1.0
	s_and_b64 vcc, exec, s[6:7]
	v_mov_b32_e32 v137, 1.0
	v_mov_b32_e32 v136, 1.0
	v_mov_b32_e32 v135, 1.0
	v_mov_b32_e32 v134, 1.0
	s_cbranch_vccnz .LBB0_821
	global_load_dwordx4 v[134:137], v[150:151], off
	s_waitcnt vmcnt(0)
.LBB0_821:
	v_mul_f32_e32 v130, v126, v217
	v_mul_f32_e32 v134, v130, v134
	v_mul_f32_e32 v130, v127, v217
	v_mul_f32_e32 v135, v130, v135
	v_mul_f32_e32 v130, v128, v217
	v_mul_f32_e32 v136, v130, v136
	v_mul_f32_e32 v130, v129, v217
	v_mul_f32_e32 v137, v130, v137
	s_and_b64 vcc, exec, s[6:7]
	v_mov_b32_e32 v132, 1.0
	v_mov_b32_e32 v131, 1.0
	v_mov_b32_e32 v130, 1.0
	ds_write_b128 v193, v[134:137]
	s_cbranch_vccnz .LBB0_823
	global_load_dwordx4 v[130:133], v[150:151], off offset:64
	s_waitcnt vmcnt(0)
.LBB0_823:
	v_mul_f32_e32 v134, v122, v217
	v_mul_f32_e32 v130, v134, v130
	v_mul_f32_e32 v134, v123, v217
	v_mul_f32_e32 v131, v134, v131
	v_mul_f32_e32 v134, v124, v217
	v_mul_f32_e32 v132, v134, v132
	v_mul_f32_e32 v134, v125, v217
	v_mul_f32_e32 v133, v134, v133
	ds_write_b128 v193, v[130:133] offset:64
	v_mov_b32_e32 v133, 1.0
	s_and_b64 vcc, exec, s[6:7]
	v_mov_b32_e32 v137, 1.0
	v_mov_b32_e32 v136, 1.0
	v_mov_b32_e32 v135, 1.0
	v_mov_b32_e32 v134, 1.0
	s_cbranch_vccnz .LBB0_825
	global_load_dwordx4 v[134:137], v[150:151], off offset:128
	s_waitcnt vmcnt(0)
.LBB0_825:
	v_mul_f32_e32 v130, v118, v217
	v_mul_f32_e32 v134, v130, v134
	v_mul_f32_e32 v130, v119, v217
	v_mul_f32_e32 v135, v130, v135
	v_mul_f32_e32 v130, v120, v217
	v_mul_f32_e32 v136, v130, v136
	v_mul_f32_e32 v130, v121, v217
	v_mul_f32_e32 v137, v130, v137
	s_and_b64 vcc, exec, s[6:7]
	v_mov_b32_e32 v132, 1.0
	v_mov_b32_e32 v131, 1.0
	v_mov_b32_e32 v130, 1.0
	ds_write_b128 v193, v[134:137] offset:128
	s_cbranch_vccnz .LBB0_827
	global_load_dwordx4 v[130:133], v[150:151], off offset:192
	s_waitcnt vmcnt(0)
.LBB0_827:
	v_mul_f32_e32 v134, v114, v217
	v_mul_f32_e32 v130, v134, v130
	v_mul_f32_e32 v134, v115, v217
	v_mul_f32_e32 v131, v134, v131
	v_mul_f32_e32 v134, v116, v217
	v_mul_f32_e32 v132, v134, v132
	v_mul_f32_e32 v134, v117, v217
	v_mul_f32_e32 v133, v134, v133
	ds_write_b128 v193, v[130:133] offset:192
	v_mov_b32_e32 v133, 1.0
	s_and_b64 vcc, exec, s[6:7]
	v_mov_b32_e32 v137, 1.0
	v_mov_b32_e32 v136, 1.0
	v_mov_b32_e32 v135, 1.0
	v_mov_b32_e32 v134, 1.0
	s_cbranch_vccnz .LBB0_829
	global_load_dwordx4 v[134:137], v[150:151], off
	s_waitcnt vmcnt(0)
.LBB0_829:
	v_mul_f32_e32 v130, v110, v216
	v_mul_f32_e32 v134, v130, v134
	v_mul_f32_e32 v130, v111, v216
	v_mul_f32_e32 v135, v130, v135
	v_mul_f32_e32 v130, v112, v216
	v_mul_f32_e32 v136, v130, v136
	v_mul_f32_e32 v130, v113, v216
	v_mul_f32_e32 v137, v130, v137
	s_and_b64 vcc, exec, s[6:7]
	v_mov_b32_e32 v132, 1.0
	v_mov_b32_e32 v131, 1.0
	v_mov_b32_e32 v130, 1.0
	ds_write_b128 v193, v[134:137] offset:16640
	s_cbranch_vccnz .LBB0_831
	global_load_dwordx4 v[130:133], v[150:151], off offset:64
	s_waitcnt vmcnt(0)
.LBB0_831:
	v_mul_f32_e32 v134, v106, v216
	v_mul_f32_e32 v130, v134, v130
	v_mul_f32_e32 v134, v107, v216
	v_mul_f32_e32 v131, v134, v131
	v_mul_f32_e32 v134, v108, v216
	v_mul_f32_e32 v132, v134, v132
	v_mul_f32_e32 v134, v109, v216
	v_mul_f32_e32 v133, v134, v133
	ds_write_b128 v193, v[130:133] offset:16704
	v_mov_b32_e32 v133, 1.0
	s_and_b64 vcc, exec, s[6:7]
	v_mov_b32_e32 v137, 1.0
	v_mov_b32_e32 v136, 1.0
	v_mov_b32_e32 v135, 1.0
	v_mov_b32_e32 v134, 1.0
	s_cbranch_vccnz .LBB0_833
	global_load_dwordx4 v[134:137], v[150:151], off offset:128
	s_waitcnt vmcnt(0)
.LBB0_833:
	v_mul_f32_e32 v130, v102, v216
	v_mul_f32_e32 v134, v130, v134
	v_mul_f32_e32 v130, v103, v216
	v_mul_f32_e32 v135, v130, v135
	v_mul_f32_e32 v130, v104, v216
	v_mul_f32_e32 v136, v130, v136
	v_mul_f32_e32 v130, v105, v216
	v_mul_f32_e32 v137, v130, v137
	s_and_b64 vcc, exec, s[6:7]
	v_mov_b32_e32 v132, 1.0
	v_mov_b32_e32 v131, 1.0
	v_mov_b32_e32 v130, 1.0
	ds_write_b128 v193, v[134:137] offset:16768
	s_cbranch_vccnz .LBB0_835
	global_load_dwordx4 v[130:133], v[150:151], off offset:192
	s_waitcnt vmcnt(0)
.LBB0_835:
	v_mul_f32_e32 v134, v98, v216
	v_mul_f32_e32 v130, v134, v130
	v_mul_f32_e32 v134, v99, v216
	v_mul_f32_e32 v131, v134, v131
	v_mul_f32_e32 v134, v100, v216
	v_mul_f32_e32 v132, v134, v132
	v_mul_f32_e32 v134, v101, v216
	v_mul_f32_e32 v133, v134, v133
	ds_write_b128 v193, v[130:133] offset:16832
	v_mov_b32_e32 v133, 1.0
	s_and_b64 vcc, exec, s[6:7]
	v_mov_b32_e32 v137, 1.0
	v_mov_b32_e32 v136, 1.0
	v_mov_b32_e32 v135, 1.0
	v_mov_b32_e32 v134, 1.0
	s_cbranch_vccnz .LBB0_837
	global_load_dwordx4 v[134:137], v[150:151], off
	s_waitcnt vmcnt(0)
.LBB0_837:
	v_mul_f32_e32 v130, v94, v215
	v_mul_f32_e32 v134, v130, v134
	v_mul_f32_e32 v130, v95, v215
	v_mul_f32_e32 v135, v130, v135
	v_mul_f32_e32 v130, v96, v215
	v_mul_f32_e32 v136, v130, v136
	v_mul_f32_e32 v130, v97, v215
	v_mul_f32_e32 v137, v130, v137
	s_and_b64 vcc, exec, s[6:7]
	v_mov_b32_e32 v132, 1.0
	v_mov_b32_e32 v131, 1.0
	v_mov_b32_e32 v130, 1.0
	ds_write_b128 v193, v[134:137] offset:33280
	s_cbranch_vccnz .LBB0_839
	global_load_dwordx4 v[130:133], v[150:151], off offset:64
	s_waitcnt vmcnt(0)
.LBB0_839:
	v_mul_f32_e32 v134, v90, v215
	v_mul_f32_e32 v130, v134, v130
	v_mul_f32_e32 v134, v91, v215
	v_mul_f32_e32 v131, v134, v131
	v_mul_f32_e32 v134, v92, v215
	v_mul_f32_e32 v132, v134, v132
	v_mul_f32_e32 v134, v93, v215
	v_mul_f32_e32 v133, v134, v133
	ds_write_b128 v193, v[130:133] offset:33344
	v_mov_b32_e32 v133, 1.0
	s_and_b64 vcc, exec, s[6:7]
	v_mov_b32_e32 v137, 1.0
	v_mov_b32_e32 v136, 1.0
	v_mov_b32_e32 v135, 1.0
	v_mov_b32_e32 v134, 1.0
	s_cbranch_vccnz .LBB0_841
	global_load_dwordx4 v[134:137], v[150:151], off offset:128
	s_waitcnt vmcnt(0)
.LBB0_841:
	v_mul_f32_e32 v130, v86, v215
	v_mul_f32_e32 v134, v130, v134
	v_mul_f32_e32 v130, v87, v215
	v_mul_f32_e32 v135, v130, v135
	v_mul_f32_e32 v130, v88, v215
	v_mul_f32_e32 v136, v130, v136
	v_mul_f32_e32 v130, v89, v215
	v_mul_f32_e32 v137, v130, v137
	s_and_b64 vcc, exec, s[6:7]
	v_mov_b32_e32 v132, 1.0
	v_mov_b32_e32 v131, 1.0
	v_mov_b32_e32 v130, 1.0
	ds_write_b128 v193, v[134:137] offset:33408
	s_cbranch_vccnz .LBB0_843
	global_load_dwordx4 v[130:133], v[150:151], off offset:192
	s_waitcnt vmcnt(0)
.LBB0_843:
	v_mul_f32_e32 v134, v82, v215
	v_mul_f32_e32 v130, v134, v130
	v_mul_f32_e32 v134, v83, v215
	v_mul_f32_e32 v131, v134, v131
	v_mul_f32_e32 v134, v84, v215
	v_mul_f32_e32 v132, v134, v132
	v_mul_f32_e32 v134, v85, v215
	v_mul_f32_e32 v133, v134, v133
	ds_write_b128 v193, v[130:133] offset:33472
	v_mov_b32_e32 v133, 1.0
	s_and_b64 vcc, exec, s[6:7]
	v_mov_b32_e32 v137, 1.0
	v_mov_b32_e32 v136, 1.0
	v_mov_b32_e32 v135, 1.0
	v_mov_b32_e32 v134, 1.0
	s_cbranch_vccnz .LBB0_845
	global_load_dwordx4 v[134:137], v[150:151], off
	s_waitcnt vmcnt(0)
.LBB0_845:
	v_mul_f32_e32 v130, v78, v214
	v_mul_f32_e32 v134, v130, v134
	v_mul_f32_e32 v130, v79, v214
	v_mul_f32_e32 v135, v130, v135
	v_mul_f32_e32 v130, v80, v214
	v_mul_f32_e32 v136, v130, v136
	v_mul_f32_e32 v130, v81, v214
	v_mul_f32_e32 v137, v130, v137
	s_and_b64 vcc, exec, s[6:7]
	v_mov_b32_e32 v132, 1.0
	v_mov_b32_e32 v131, 1.0
	v_mov_b32_e32 v130, 1.0
	ds_write_b128 v193, v[134:137] offset:49920
	s_cbranch_vccnz .LBB0_847
	global_load_dwordx4 v[130:133], v[150:151], off offset:64
	s_waitcnt vmcnt(0)
.LBB0_847:
	v_mul_f32_e32 v134, v74, v214
	v_mul_f32_e32 v130, v134, v130
	v_mul_f32_e32 v134, v75, v214
	v_mul_f32_e32 v131, v134, v131
	v_mul_f32_e32 v134, v76, v214
	v_mul_f32_e32 v132, v134, v132
	v_mul_f32_e32 v134, v77, v214
	v_mul_f32_e32 v133, v134, v133
	ds_write_b128 v193, v[130:133] offset:49984
	v_mov_b32_e32 v133, 1.0
	s_and_b64 vcc, exec, s[6:7]
	v_mov_b32_e32 v137, 1.0
	v_mov_b32_e32 v136, 1.0
	v_mov_b32_e32 v135, 1.0
	v_mov_b32_e32 v134, 1.0
	s_cbranch_vccnz .LBB0_849
	global_load_dwordx4 v[134:137], v[150:151], off offset:128
	s_waitcnt vmcnt(0)
.LBB0_849:
	v_mul_f32_e32 v130, v70, v214
	v_mul_f32_e32 v134, v130, v134
	v_mul_f32_e32 v130, v71, v214
	v_mul_f32_e32 v135, v130, v135
	v_mul_f32_e32 v130, v72, v214
	v_mul_f32_e32 v136, v130, v136
	v_mul_f32_e32 v130, v73, v214
	v_mul_f32_e32 v137, v130, v137
	s_and_b64 vcc, exec, s[6:7]
	v_mov_b32_e32 v132, 1.0
	v_mov_b32_e32 v131, 1.0
	v_mov_b32_e32 v130, 1.0
	ds_write_b128 v193, v[134:137] offset:50048
	s_cbranch_vccnz .LBB0_851
	global_load_dwordx4 v[130:133], v[150:151], off offset:192
	s_waitcnt vmcnt(0)
.LBB0_851:
	v_mul_f32_e32 v134, v66, v214
	v_mul_f32_e32 v130, v134, v130
	v_mul_f32_e32 v134, v67, v214
	v_mul_f32_e32 v131, v134, v131
	v_mul_f32_e32 v134, v68, v214
	v_mul_f32_e32 v132, v134, v132
	v_mul_f32_e32 v134, v69, v214
	v_mul_f32_e32 v133, v134, v133
	ds_write_b128 v193, v[130:133] offset:50112
	v_mov_b32_e32 v133, 1.0
	s_and_b64 vcc, exec, s[6:7]
	v_mov_b32_e32 v137, 1.0
	v_mov_b32_e32 v136, 1.0
	v_mov_b32_e32 v135, 1.0
	v_mov_b32_e32 v134, 1.0
	s_cbranch_vccnz .LBB0_853
	global_load_dwordx4 v[134:137], v[150:151], off
	s_waitcnt vmcnt(0)
.LBB0_853:
	v_mul_f32_e32 v130, v62, v213
	v_mul_f32_e32 v134, v130, v134
	v_mul_f32_e32 v130, v63, v213
	v_mul_f32_e32 v135, v130, v135
	v_mul_f32_e32 v130, v64, v213
	v_mul_f32_e32 v136, v130, v136
	v_mul_f32_e32 v130, v65, v213
	v_mul_f32_e32 v137, v130, v137
	v_add_u32_e32 v130, v197, v192
	ds_write_b128 v130, v[134:137]
	s_and_b64 vcc, exec, s[6:7]
	v_mov_b32_e32 v132, 1.0
	v_mov_b32_e32 v131, 1.0
	v_mov_b32_e32 v130, 1.0
	s_cbranch_vccnz .LBB0_855
	global_load_dwordx4 v[130:133], v[150:151], off offset:64
	s_waitcnt vmcnt(0)
.LBB0_855:
	v_mul_f32_e32 v134, v58, v213
	v_mul_f32_e32 v130, v134, v130
	v_mul_f32_e32 v134, v59, v213
	v_mul_f32_e32 v131, v134, v131
	v_mul_f32_e32 v134, v60, v213
	v_mul_f32_e32 v132, v134, v132
	v_mul_f32_e32 v134, v61, v213
	v_mul_f32_e32 v133, v134, v133
	v_add_u32_e32 v134, v197, v194
	ds_write_b128 v134, v[130:133]
	v_mov_b32_e32 v133, 1.0
	s_and_b64 vcc, exec, s[6:7]
	v_mov_b32_e32 v137, 1.0
	v_mov_b32_e32 v136, 1.0
	v_mov_b32_e32 v135, 1.0
	v_mov_b32_e32 v134, 1.0
	s_cbranch_vccnz .LBB0_857
	global_load_dwordx4 v[134:137], v[150:151], off offset:128
	s_waitcnt vmcnt(0)
.LBB0_857:
	v_mul_f32_e32 v130, v54, v213
	v_mul_f32_e32 v134, v130, v134
	v_mul_f32_e32 v130, v55, v213
	v_mul_f32_e32 v135, v130, v135
	v_mul_f32_e32 v130, v56, v213
	v_mul_f32_e32 v136, v130, v136
	v_mul_f32_e32 v130, v57, v213
	v_mul_f32_e32 v137, v130, v137
	v_add_u32_e32 v130, v197, v195
	ds_write_b128 v130, v[134:137]
	s_and_b64 vcc, exec, s[6:7]
	v_mov_b32_e32 v132, 1.0
	v_mov_b32_e32 v131, 1.0
	v_mov_b32_e32 v130, 1.0
	s_cbranch_vccnz .LBB0_859
	global_load_dwordx4 v[130:133], v[150:151], off offset:192
	s_waitcnt vmcnt(0)
.LBB0_859:
	v_mul_f32_e32 v134, v50, v213
	v_mul_f32_e32 v130, v134, v130
	v_mul_f32_e32 v134, v51, v213
	v_mul_f32_e32 v131, v134, v131
	v_mul_f32_e32 v134, v52, v213
	v_mul_f32_e32 v132, v134, v132
	v_mul_f32_e32 v134, v53, v213
	v_mul_f32_e32 v133, v134, v133
	v_add_u32_e32 v134, v197, v196
	ds_write_b128 v134, v[130:133]
	v_mov_b32_e32 v133, 1.0
	s_and_b64 vcc, exec, s[6:7]
	v_mov_b32_e32 v137, 1.0
	v_mov_b32_e32 v136, 1.0
	v_mov_b32_e32 v135, 1.0
	v_mov_b32_e32 v134, 1.0
	s_cbranch_vccnz .LBB0_861
	global_load_dwordx4 v[134:137], v[150:151], off
	s_waitcnt vmcnt(0)
.LBB0_861:
	v_mul_f32_e32 v130, v46, v212
	v_mul_f32_e32 v134, v130, v134
	v_mul_f32_e32 v130, v47, v212
	v_mul_f32_e32 v135, v130, v135
	v_mul_f32_e32 v130, v48, v212
	v_mul_f32_e32 v136, v130, v136
	v_mul_f32_e32 v130, v49, v212
	v_mul_f32_e32 v137, v130, v137
	v_add_u32_e32 v130, v198, v192
	ds_write_b128 v130, v[134:137]
	s_and_b64 vcc, exec, s[6:7]
	v_mov_b32_e32 v132, 1.0
	v_mov_b32_e32 v131, 1.0
	v_mov_b32_e32 v130, 1.0
	s_cbranch_vccnz .LBB0_863
	global_load_dwordx4 v[130:133], v[150:151], off offset:64
	s_waitcnt vmcnt(0)
.LBB0_863:
	v_mul_f32_e32 v134, v42, v212
	v_mul_f32_e32 v130, v134, v130
	v_mul_f32_e32 v134, v43, v212
	v_mul_f32_e32 v131, v134, v131
	v_mul_f32_e32 v134, v44, v212
	v_mul_f32_e32 v132, v134, v132
	v_mul_f32_e32 v134, v45, v212
	v_mul_f32_e32 v133, v134, v133
	v_add_u32_e32 v134, v198, v194
	ds_write_b128 v134, v[130:133]
	v_mov_b32_e32 v133, 1.0
	s_and_b64 vcc, exec, s[6:7]
	v_mov_b32_e32 v137, 1.0
	v_mov_b32_e32 v136, 1.0
	v_mov_b32_e32 v135, 1.0
	v_mov_b32_e32 v134, 1.0
	s_cbranch_vccnz .LBB0_865
	global_load_dwordx4 v[134:137], v[150:151], off offset:128
	s_waitcnt vmcnt(0)
.LBB0_865:
	v_mul_f32_e32 v130, v38, v212
	v_mul_f32_e32 v134, v130, v134
	v_mul_f32_e32 v130, v39, v212
	v_mul_f32_e32 v135, v130, v135
	v_mul_f32_e32 v130, v40, v212
	v_mul_f32_e32 v136, v130, v136
	v_mul_f32_e32 v130, v41, v212
	v_mul_f32_e32 v137, v130, v137
	v_add_u32_e32 v130, v198, v195
	ds_write_b128 v130, v[134:137]
	s_and_b64 vcc, exec, s[6:7]
	v_mov_b32_e32 v132, 1.0
	v_mov_b32_e32 v131, 1.0
	v_mov_b32_e32 v130, 1.0
	s_cbranch_vccnz .LBB0_867
	global_load_dwordx4 v[130:133], v[150:151], off offset:192
	s_waitcnt vmcnt(0)
.LBB0_867:
	v_mul_f32_e32 v134, v34, v212
	v_mul_f32_e32 v130, v134, v130
	v_mul_f32_e32 v134, v35, v212
	v_mul_f32_e32 v131, v134, v131
	v_mul_f32_e32 v134, v36, v212
	v_mul_f32_e32 v132, v134, v132
	v_mul_f32_e32 v134, v37, v212
	v_mul_f32_e32 v133, v134, v133
	v_add_u32_e32 v134, v198, v196
	ds_write_b128 v134, v[130:133]
	v_mov_b32_e32 v133, 1.0
	s_and_b64 vcc, exec, s[6:7]
	v_mov_b32_e32 v137, 1.0
	v_mov_b32_e32 v136, 1.0
	v_mov_b32_e32 v135, 1.0
	v_mov_b32_e32 v134, 1.0
	s_cbranch_vccnz .LBB0_869
	global_load_dwordx4 v[134:137], v[150:151], off
	s_waitcnt vmcnt(0)
.LBB0_869:
	v_mul_f32_e32 v130, v30, v211
	v_mul_f32_e32 v134, v130, v134
	v_mul_f32_e32 v130, v31, v211
	v_mul_f32_e32 v135, v130, v135
	v_mul_f32_e32 v130, v32, v211
	v_mul_f32_e32 v136, v130, v136
	v_mul_f32_e32 v130, v33, v211
	v_mul_f32_e32 v137, v130, v137
	v_add_u32_e32 v130, v199, v192
	ds_write_b128 v130, v[134:137]
	s_and_b64 vcc, exec, s[6:7]
	v_mov_b32_e32 v132, 1.0
	v_mov_b32_e32 v131, 1.0
	v_mov_b32_e32 v130, 1.0
	s_cbranch_vccnz .LBB0_871
	global_load_dwordx4 v[130:133], v[150:151], off offset:64
	s_waitcnt vmcnt(0)
.LBB0_871:
	v_mul_f32_e32 v134, v26, v211
	v_mul_f32_e32 v130, v134, v130
	v_mul_f32_e32 v134, v27, v211
	v_mul_f32_e32 v131, v134, v131
	v_mul_f32_e32 v134, v28, v211
	v_mul_f32_e32 v132, v134, v132
	v_mul_f32_e32 v134, v29, v211
	v_mul_f32_e32 v133, v134, v133
	v_add_u32_e32 v134, v199, v194
	ds_write_b128 v134, v[130:133]
	v_mov_b32_e32 v133, 1.0
	s_and_b64 vcc, exec, s[6:7]
	v_mov_b32_e32 v137, 1.0
	v_mov_b32_e32 v136, 1.0
	v_mov_b32_e32 v135, 1.0
	v_mov_b32_e32 v134, 1.0
	s_cbranch_vccnz .LBB0_873
	global_load_dwordx4 v[134:137], v[150:151], off offset:128
	s_waitcnt vmcnt(0)
.LBB0_873:
	v_mul_f32_e32 v130, v22, v211
	v_mul_f32_e32 v134, v130, v134
	v_mul_f32_e32 v130, v23, v211
	v_mul_f32_e32 v135, v130, v135
	v_mul_f32_e32 v130, v24, v211
	v_mul_f32_e32 v136, v130, v136
	v_mul_f32_e32 v130, v25, v211
	v_mul_f32_e32 v137, v130, v137
	v_add_u32_e32 v130, v199, v195
	ds_write_b128 v130, v[134:137]
	s_and_b64 vcc, exec, s[6:7]
	v_mov_b32_e32 v132, 1.0
	v_mov_b32_e32 v131, 1.0
	v_mov_b32_e32 v130, 1.0
	s_cbranch_vccnz .LBB0_875
	global_load_dwordx4 v[130:133], v[150:151], off offset:192
	s_waitcnt vmcnt(0)
.LBB0_875:
	v_mul_f32_e32 v134, v18, v211
	v_mul_f32_e32 v130, v134, v130
	v_mul_f32_e32 v134, v19, v211
	v_mul_f32_e32 v131, v134, v131
	v_mul_f32_e32 v134, v20, v211
	v_mul_f32_e32 v132, v134, v132
	v_mul_f32_e32 v134, v21, v211
	v_mul_f32_e32 v133, v134, v133
	v_add_u32_e32 v134, v199, v196
	ds_write_b128 v134, v[130:133]
	v_mov_b32_e32 v133, 1.0
	s_and_b64 vcc, exec, s[6:7]
	v_mov_b32_e32 v137, 1.0
	v_mov_b32_e32 v136, 1.0
	v_mov_b32_e32 v135, 1.0
	v_mov_b32_e32 v134, 1.0
	s_cbranch_vccnz .LBB0_877
	global_load_dwordx4 v[134:137], v[150:151], off
	s_waitcnt vmcnt(0)
.LBB0_877:
	v_mul_f32_e32 v130, v14, v210
	v_mul_f32_e32 v134, v130, v134
	v_mul_f32_e32 v130, v15, v210
	v_mul_f32_e32 v135, v130, v135
	v_mul_f32_e32 v130, v16, v210
	v_mul_f32_e32 v136, v130, v136
	v_mul_f32_e32 v130, v17, v210
	v_mul_f32_e32 v137, v130, v137
	v_add_u32_e32 v130, v200, v192
	ds_write_b128 v130, v[134:137]
	s_and_b64 vcc, exec, s[6:7]
	v_mov_b32_e32 v132, 1.0
	v_mov_b32_e32 v131, 1.0
	v_mov_b32_e32 v130, 1.0
	s_cbranch_vccnz .LBB0_879
	global_load_dwordx4 v[130:133], v[150:151], off offset:64
	s_waitcnt vmcnt(0)
.LBB0_879:
	v_mul_f32_e32 v134, v10, v210
	v_mul_f32_e32 v130, v134, v130
	v_mul_f32_e32 v134, v11, v210
	v_mul_f32_e32 v131, v134, v131
	v_mul_f32_e32 v134, v12, v210
	v_mul_f32_e32 v132, v134, v132
	v_mul_f32_e32 v134, v13, v210
	v_mul_f32_e32 v133, v134, v133
	v_add_u32_e32 v134, v200, v194
	ds_write_b128 v134, v[130:133]
	v_mov_b32_e32 v133, 1.0
	s_and_b64 vcc, exec, s[6:7]
	v_mov_b32_e32 v137, 1.0
	v_mov_b32_e32 v136, 1.0
	v_mov_b32_e32 v135, 1.0
	v_mov_b32_e32 v134, 1.0
	s_cbranch_vccnz .LBB0_881
	global_load_dwordx4 v[134:137], v[150:151], off offset:128
	s_waitcnt vmcnt(0)
.LBB0_881:
	v_mul_f32_e32 v130, v6, v210
	v_mul_f32_e32 v134, v130, v134
	v_mul_f32_e32 v130, v7, v210
	v_mul_f32_e32 v135, v130, v135
	v_mul_f32_e32 v130, v8, v210
	v_mul_f32_e32 v136, v130, v136
	v_mul_f32_e32 v130, v9, v210
	v_mul_f32_e32 v137, v130, v137
	v_add_u32_e32 v130, v200, v195
	ds_write_b128 v130, v[134:137]
	s_and_b64 vcc, exec, s[6:7]
	v_mov_b32_e32 v132, 1.0
	v_mov_b32_e32 v131, 1.0
	v_mov_b32_e32 v130, 1.0
	s_cbranch_vccnz .LBB0_883
	global_load_dwordx4 v[130:133], v[150:151], off offset:192
	s_waitcnt vmcnt(0)
.LBB0_883:
	v_mul_f32_e32 v134, v2, v210
	v_mul_f32_e32 v130, v134, v130
	v_mul_f32_e32 v134, v3, v210
	v_mul_f32_e32 v131, v134, v131
	v_mul_f32_e32 v134, v4, v210
	v_mul_f32_e32 v132, v134, v132
	v_mul_f32_e32 v134, v5, v210
	v_mul_f32_e32 v133, v134, v133
	v_add_u32_e32 v134, v200, v196
	ds_write_b128 v134, v[130:133]

.LBB0_885:
	ds_read_b128 v[140:143], v135
	ds_read_b128 v[218:221], v134
	ds_read_b128 v[222:225], v134 offset:16640
	ds_read_b128 v[226:229], v138
	v_lshl_add_u64 v[144:145], v[136:137], 0, s[44:45]
	v_lshl_add_u64 v[230:231], v[132:133], 0, s[44:45]
	v_lshl_add_u64 v[232:233], v[130:131], 0, s[44:45]
	s_add_u32 s44, s44, 0x40000
	s_addc_u32 s45, s45, 0
	v_add_u32_e32 v138, 0x8200, v138
	v_add_u32_e32 v135, 0x8200, v135
	v_add_u32_e32 v134, 0x8200, v134
	v_add_co_u32_e32 v234, vcc, 0x20000, v144
	s_cmp_eq_u32 s44, 0x100000
	s_nop 0
	v_addc_co_u32_e32 v235, vcc, 0, v145, vcc
	s_waitcnt lgkmcnt(2)
	global_store_dwordx4 v[144:145], v[218:221], off nt
	global_store_dwordx4 v[230:231], v[140:143], off nt
	s_waitcnt lgkmcnt(1)
	global_store_dwordx4 v[234:235], v[222:225], off nt
	s_waitcnt lgkmcnt(0)
	global_store_dwordx4 v[232:233], v[226:229], off nt
	s_cbranch_scc0 .LBB0_885
	s_barrier
	s_and_saveexec_b64 s[44:45], s[4:5]
	s_cbranch_execz .LBB0_952
	v_mov_b32_e32 v131, 1.0
	s_and_b64 vcc, exec, s[6:7]
	v_mov_b32_e32 v135, 1.0
	v_mov_b32_e32 v134, 1.0
	v_mov_b32_e32 v133, 1.0
	v_mov_b32_e32 v132, 1.0
	s_cbranch_vccnz .LBB0_889
	global_load_dwordx4 v[132:135], v[150:151], off
	s_waitcnt vmcnt(0)
.LBB0_889:
	v_mul_f32_e32 v126, v126, v217
	v_mul_f32_e32 v127, v127, v217
	v_mul_f32_e32 v128, v128, v217
	v_mul_f32_e32 v129, v129, v217
	v_mul_f32_e32 v126, v126, v132
	v_mul_f32_e32 v127, v127, v133
	v_mul_f32_e32 v128, v128, v134
	v_mul_f32_e32 v129, v129, v135
	ds_write_b128 v193, v[126:129]
	s_and_b64 vcc, exec, s[6:7]
	v_mov_b32_e32 v130, 1.0
	v_mov_b32_e32 v129, 1.0
	v_mov_b32_e32 v128, 1.0
	s_cbranch_vccnz .LBB0_891
	global_load_dwordx4 v[128:131], v[150:151], off offset:64
	s_waitcnt vmcnt(0)
.LBB0_891:
	v_mul_f32_e32 v122, v122, v217
	v_mul_f32_e32 v123, v123, v217
	v_mul_f32_e32 v124, v124, v217
	v_mul_f32_e32 v125, v125, v217
	v_mul_f32_e32 v122, v122, v128
	v_mul_f32_e32 v123, v123, v129
	v_mul_f32_e32 v124, v124, v130
	v_mul_f32_e32 v125, v125, v131
	ds_write_b128 v193, v[122:125] offset:64
	v_mov_b32_e32 v123, 1.0
	s_and_b64 vcc, exec, s[6:7]
	v_mov_b32_e32 v127, 1.0
	v_mov_b32_e32 v126, 1.0
	v_mov_b32_e32 v125, 1.0
	v_mov_b32_e32 v124, 1.0
	s_cbranch_vccnz .LBB0_893
	global_load_dwordx4 v[124:127], v[150:151], off offset:128
	s_waitcnt vmcnt(0)
.LBB0_893:
	v_mul_f32_e32 v118, v118, v217
	v_mul_f32_e32 v119, v119, v217
	v_mul_f32_e32 v120, v120, v217
	v_mul_f32_e32 v121, v121, v217
	v_mul_f32_e32 v118, v118, v124
	v_mul_f32_e32 v119, v119, v125
	v_mul_f32_e32 v120, v120, v126
	v_mul_f32_e32 v121, v121, v127
	ds_write_b128 v193, v[118:121] offset:128
	s_and_b64 vcc, exec, s[6:7]
	v_mov_b32_e32 v122, 1.0
	v_mov_b32_e32 v121, 1.0
	v_mov_b32_e32 v120, 1.0
	s_cbranch_vccnz .LBB0_895
	global_load_dwordx4 v[120:123], v[150:151], off offset:192
	s_waitcnt vmcnt(0)
.LBB0_895:
	v_mul_f32_e32 v114, v114, v217
	v_mul_f32_e32 v115, v115, v217
	v_mul_f32_e32 v116, v116, v217
	v_mul_f32_e32 v117, v117, v217
	v_mul_f32_e32 v114, v114, v120
	v_mul_f32_e32 v115, v115, v121
	v_mul_f32_e32 v116, v116, v122
	v_mul_f32_e32 v117, v117, v123
	ds_write_b128 v193, v[114:117] offset:192
	v_mov_b32_e32 v115, 1.0
	s_and_b64 vcc, exec, s[6:7]
	v_mov_b32_e32 v119, 1.0
	v_mov_b32_e32 v118, 1.0
	v_mov_b32_e32 v117, 1.0
	v_mov_b32_e32 v116, 1.0
	s_cbranch_vccnz .LBB0_897
	global_load_dwordx4 v[116:119], v[150:151], off
	s_waitcnt vmcnt(0)
.LBB0_897:
	v_mul_f32_e32 v110, v110, v216
	v_mul_f32_e32 v111, v111, v216
	v_mul_f32_e32 v112, v112, v216
	v_mul_f32_e32 v113, v113, v216
	v_mul_f32_e32 v110, v110, v116
	v_mul_f32_e32 v111, v111, v117
	v_mul_f32_e32 v112, v112, v118
	v_mul_f32_e32 v113, v113, v119
	ds_write_b128 v193, v[110:113] offset:16640
	s_and_b64 vcc, exec, s[6:7]
	v_mov_b32_e32 v114, 1.0
	v_mov_b32_e32 v113, 1.0
	v_mov_b32_e32 v112, 1.0
	s_cbranch_vccnz .LBB0_899
	global_load_dwordx4 v[112:115], v[150:151], off offset:64
	s_waitcnt vmcnt(0)
.LBB0_899:
	v_mul_f32_e32 v106, v106, v216
	v_mul_f32_e32 v107, v107, v216
	v_mul_f32_e32 v108, v108, v216
	v_mul_f32_e32 v109, v109, v216
	v_mul_f32_e32 v106, v106, v112
	v_mul_f32_e32 v107, v107, v113
	v_mul_f32_e32 v108, v108, v114
	v_mul_f32_e32 v109, v109, v115
	ds_write_b128 v193, v[106:109] offset:16704
	v_mov_b32_e32 v107, 1.0
	s_and_b64 vcc, exec, s[6:7]
	v_mov_b32_e32 v111, 1.0
	v_mov_b32_e32 v110, 1.0
	v_mov_b32_e32 v109, 1.0
	v_mov_b32_e32 v108, 1.0
	s_cbranch_vccnz .LBB0_901
	global_load_dwordx4 v[108:111], v[150:151], off offset:128
	s_waitcnt vmcnt(0)
.LBB0_901:
	v_mul_f32_e32 v102, v102, v216
	v_mul_f32_e32 v103, v103, v216
	v_mul_f32_e32 v104, v104, v216
	v_mul_f32_e32 v105, v105, v216
	v_mul_f32_e32 v102, v102, v108
	v_mul_f32_e32 v103, v103, v109
	v_mul_f32_e32 v104, v104, v110
	v_mul_f32_e32 v105, v105, v111
	ds_write_b128 v193, v[102:105] offset:16768
	s_and_b64 vcc, exec, s[6:7]
	v_mov_b32_e32 v106, 1.0
	v_mov_b32_e32 v105, 1.0
	v_mov_b32_e32 v104, 1.0
	s_cbranch_vccnz .LBB0_903
	global_load_dwordx4 v[104:107], v[150:151], off offset:192
	s_waitcnt vmcnt(0)
.LBB0_903:
	v_mul_f32_e32 v98, v98, v216
	v_mul_f32_e32 v99, v99, v216
	v_mul_f32_e32 v100, v100, v216
	v_mul_f32_e32 v101, v101, v216
	v_mul_f32_e32 v98, v98, v104
	v_mul_f32_e32 v99, v99, v105
	v_mul_f32_e32 v100, v100, v106
	v_mul_f32_e32 v101, v101, v107
	ds_write_b128 v193, v[98:101] offset:16832
	v_mov_b32_e32 v99, 1.0
	s_and_b64 vcc, exec, s[6:7]
	v_mov_b32_e32 v103, 1.0
	v_mov_b32_e32 v102, 1.0
	v_mov_b32_e32 v101, 1.0
	v_mov_b32_e32 v100, 1.0
	s_cbranch_vccnz .LBB0_905
	global_load_dwordx4 v[100:103], v[150:151], off
	s_waitcnt vmcnt(0)
.LBB0_905:
	v_mul_f32_e32 v94, v94, v215
	v_mul_f32_e32 v95, v95, v215
	v_mul_f32_e32 v96, v96, v215
	v_mul_f32_e32 v97, v97, v215
	v_mul_f32_e32 v94, v94, v100
	v_mul_f32_e32 v95, v95, v101
	v_mul_f32_e32 v96, v96, v102
	v_mul_f32_e32 v97, v97, v103
	ds_write_b128 v193, v[94:97] offset:33280
	s_and_b64 vcc, exec, s[6:7]
	v_mov_b32_e32 v98, 1.0
	v_mov_b32_e32 v97, 1.0
	v_mov_b32_e32 v96, 1.0
	s_cbranch_vccnz .LBB0_907
	global_load_dwordx4 v[96:99], v[150:151], off offset:64
	s_waitcnt vmcnt(0)
.LBB0_907:
	v_mul_f32_e32 v90, v90, v215
	v_mul_f32_e32 v91, v91, v215
	v_mul_f32_e32 v92, v92, v215
	v_mul_f32_e32 v93, v93, v215
	v_mul_f32_e32 v90, v90, v96
	v_mul_f32_e32 v91, v91, v97
	v_mul_f32_e32 v92, v92, v98
	v_mul_f32_e32 v93, v93, v99
	ds_write_b128 v193, v[90:93] offset:33344
	v_mov_b32_e32 v91, 1.0
	s_and_b64 vcc, exec, s[6:7]
	v_mov_b32_e32 v95, 1.0
	v_mov_b32_e32 v94, 1.0
	v_mov_b32_e32 v93, 1.0
	v_mov_b32_e32 v92, 1.0
	s_cbranch_vccnz .LBB0_909
	global_load_dwordx4 v[92:95], v[150:151], off offset:128
	s_waitcnt vmcnt(0)
.LBB0_909:
	v_mul_f32_e32 v86, v86, v215
	v_mul_f32_e32 v87, v87, v215
	v_mul_f32_e32 v88, v88, v215
	v_mul_f32_e32 v89, v89, v215
	v_mul_f32_e32 v86, v86, v92
	v_mul_f32_e32 v87, v87, v93
	v_mul_f32_e32 v88, v88, v94
	v_mul_f32_e32 v89, v89, v95
	ds_write_b128 v193, v[86:89] offset:33408
	s_and_b64 vcc, exec, s[6:7]
	v_mov_b32_e32 v90, 1.0
	v_mov_b32_e32 v89, 1.0
	v_mov_b32_e32 v88, 1.0
	s_cbranch_vccnz .LBB0_911
	global_load_dwordx4 v[88:91], v[150:151], off offset:192
	s_waitcnt vmcnt(0)
.LBB0_911:
	v_mul_f32_e32 v82, v82, v215
	v_mul_f32_e32 v83, v83, v215
	v_mul_f32_e32 v84, v84, v215
	v_mul_f32_e32 v85, v85, v215
	v_mul_f32_e32 v82, v82, v88
	v_mul_f32_e32 v83, v83, v89
	v_mul_f32_e32 v84, v84, v90
	v_mul_f32_e32 v85, v85, v91
	ds_write_b128 v193, v[82:85] offset:33472
	v_mov_b32_e32 v83, 1.0
	s_and_b64 vcc, exec, s[6:7]
	v_mov_b32_e32 v87, 1.0
	v_mov_b32_e32 v86, 1.0
	v_mov_b32_e32 v85, 1.0
	v_mov_b32_e32 v84, 1.0
	s_cbranch_vccnz .LBB0_913
	global_load_dwordx4 v[84:87], v[150:151], off
	s_waitcnt vmcnt(0)
.LBB0_913:
	v_mul_f32_e32 v78, v78, v214
	v_mul_f32_e32 v79, v79, v214
	v_mul_f32_e32 v80, v80, v214
	v_mul_f32_e32 v81, v81, v214
	v_mul_f32_e32 v78, v78, v84
	v_mul_f32_e32 v79, v79, v85
	v_mul_f32_e32 v80, v80, v86
	v_mul_f32_e32 v81, v81, v87
	ds_write_b128 v193, v[78:81] offset:49920
	s_and_b64 vcc, exec, s[6:7]
	v_mov_b32_e32 v82, 1.0
	v_mov_b32_e32 v81, 1.0
	v_mov_b32_e32 v80, 1.0
	s_cbranch_vccnz .LBB0_915
	global_load_dwordx4 v[80:83], v[150:151], off offset:64
	s_waitcnt vmcnt(0)
.LBB0_915:
	v_mul_f32_e32 v74, v74, v214
	v_mul_f32_e32 v75, v75, v214
	v_mul_f32_e32 v76, v76, v214
	v_mul_f32_e32 v77, v77, v214
	v_mul_f32_e32 v74, v74, v80
	v_mul_f32_e32 v75, v75, v81
	v_mul_f32_e32 v76, v76, v82
	v_mul_f32_e32 v77, v77, v83
	ds_write_b128 v193, v[74:77] offset:49984
	v_mov_b32_e32 v75, 1.0
	s_and_b64 vcc, exec, s[6:7]
	v_mov_b32_e32 v79, 1.0
	v_mov_b32_e32 v78, 1.0
	v_mov_b32_e32 v77, 1.0
	v_mov_b32_e32 v76, 1.0
	s_cbranch_vccnz .LBB0_917
	global_load_dwordx4 v[76:79], v[150:151], off offset:128
	s_waitcnt vmcnt(0)
.LBB0_917:
	v_mul_f32_e32 v70, v70, v214
	v_mul_f32_e32 v71, v71, v214
	v_mul_f32_e32 v72, v72, v214
	v_mul_f32_e32 v73, v73, v214
	v_mul_f32_e32 v70, v70, v76
	v_mul_f32_e32 v71, v71, v77
	v_mul_f32_e32 v72, v72, v78
	v_mul_f32_e32 v73, v73, v79
	ds_write_b128 v193, v[70:73] offset:50048
	s_and_b64 vcc, exec, s[6:7]
	v_mov_b32_e32 v74, 1.0
	v_mov_b32_e32 v73, 1.0
	v_mov_b32_e32 v72, 1.0
	s_cbranch_vccnz .LBB0_919
	global_load_dwordx4 v[72:75], v[150:151], off offset:192
	s_waitcnt vmcnt(0)
.LBB0_919:
	v_mul_f32_e32 v66, v66, v214
	v_mul_f32_e32 v67, v67, v214
	v_mul_f32_e32 v68, v68, v214
	v_mul_f32_e32 v69, v69, v214
	v_mul_f32_e32 v66, v66, v72
	v_mul_f32_e32 v67, v67, v73
	v_mul_f32_e32 v68, v68, v74
	v_mul_f32_e32 v69, v69, v75
	ds_write_b128 v193, v[66:69] offset:50112
	v_mov_b32_e32 v67, 1.0
	s_and_b64 vcc, exec, s[6:7]
	v_mov_b32_e32 v71, 1.0
	v_mov_b32_e32 v70, 1.0
	v_mov_b32_e32 v69, 1.0
	v_mov_b32_e32 v68, 1.0
	s_cbranch_vccnz .LBB0_921
	global_load_dwordx4 v[68:71], v[150:151], off
	s_waitcnt vmcnt(0)
.LBB0_921:
	v_mul_f32_e32 v62, v62, v213
	v_mul_f32_e32 v63, v63, v213
	v_mul_f32_e32 v64, v64, v213
	v_mul_f32_e32 v65, v65, v213
	v_mul_f32_e32 v62, v62, v68
	v_mul_f32_e32 v63, v63, v69
	v_mul_f32_e32 v64, v64, v70
	v_mul_f32_e32 v65, v65, v71
	v_add_u32_e32 v66, v197, v192
	ds_write_b128 v66, v[62:65]
	s_and_b64 vcc, exec, s[6:7]
	v_mov_b32_e32 v66, 1.0
	v_mov_b32_e32 v65, 1.0
	v_mov_b32_e32 v64, 1.0
	s_cbranch_vccnz .LBB0_923
	global_load_dwordx4 v[64:67], v[150:151], off offset:64
	s_waitcnt vmcnt(0)
.LBB0_923:
	v_mul_f32_e32 v58, v58, v213
	v_mul_f32_e32 v59, v59, v213
	v_mul_f32_e32 v60, v60, v213
	v_mul_f32_e32 v61, v61, v213
	v_mul_f32_e32 v58, v58, v64
	v_mul_f32_e32 v59, v59, v65
	v_mul_f32_e32 v60, v60, v66
	v_mul_f32_e32 v61, v61, v67
	v_add_u32_e32 v62, v197, v194
	ds_write_b128 v62, v[58:61]
	v_mov_b32_e32 v59, 1.0
	s_and_b64 vcc, exec, s[6:7]
	v_mov_b32_e32 v63, 1.0
	v_mov_b32_e32 v62, 1.0
	v_mov_b32_e32 v61, 1.0
	v_mov_b32_e32 v60, 1.0
	s_cbranch_vccnz .LBB0_925
	global_load_dwordx4 v[60:63], v[150:151], off offset:128
	s_waitcnt vmcnt(0)
.LBB0_925:
	v_mul_f32_e32 v54, v54, v213
	v_mul_f32_e32 v55, v55, v213
	v_mul_f32_e32 v56, v56, v213
	v_mul_f32_e32 v57, v57, v213
	v_mul_f32_e32 v54, v54, v60
	v_mul_f32_e32 v55, v55, v61
	v_mul_f32_e32 v56, v56, v62
	v_mul_f32_e32 v57, v57, v63
	v_add_u32_e32 v58, v197, v195
	ds_write_b128 v58, v[54:57]
	s_and_b64 vcc, exec, s[6:7]
	v_mov_b32_e32 v58, 1.0
	v_mov_b32_e32 v57, 1.0
	v_mov_b32_e32 v56, 1.0
	s_cbranch_vccnz .LBB0_927
	global_load_dwordx4 v[56:59], v[150:151], off offset:192
	s_waitcnt vmcnt(0)
.LBB0_927:
	v_mul_f32_e32 v50, v50, v213
	v_mul_f32_e32 v51, v51, v213
	v_mul_f32_e32 v52, v52, v213
	v_mul_f32_e32 v53, v53, v213
	v_mul_f32_e32 v50, v50, v56
	v_mul_f32_e32 v51, v51, v57
	v_mul_f32_e32 v52, v52, v58
	v_mul_f32_e32 v53, v53, v59
	v_add_u32_e32 v54, v197, v196
	ds_write_b128 v54, v[50:53]
	v_mov_b32_e32 v51, 1.0
	s_and_b64 vcc, exec, s[6:7]
	v_mov_b32_e32 v55, 1.0
	v_mov_b32_e32 v54, 1.0
	v_mov_b32_e32 v53, 1.0
	v_mov_b32_e32 v52, 1.0
	s_cbranch_vccnz .LBB0_929
	global_load_dwordx4 v[52:55], v[150:151], off
	s_waitcnt vmcnt(0)
.LBB0_929:
	v_mul_f32_e32 v46, v46, v212
	v_mul_f32_e32 v47, v47, v212
	v_mul_f32_e32 v48, v48, v212
	v_mul_f32_e32 v49, v49, v212
	v_mul_f32_e32 v46, v46, v52
	v_mul_f32_e32 v47, v47, v53
	v_mul_f32_e32 v48, v48, v54
	v_mul_f32_e32 v49, v49, v55
	v_add_u32_e32 v50, v198, v192
	ds_write_b128 v50, v[46:49]
	s_and_b64 vcc, exec, s[6:7]
	v_mov_b32_e32 v50, 1.0
	v_mov_b32_e32 v49, 1.0
	v_mov_b32_e32 v48, 1.0
	s_cbranch_vccnz .LBB0_931
	global_load_dwordx4 v[48:51], v[150:151], off offset:64
	s_waitcnt vmcnt(0)
.LBB0_931:
	v_mul_f32_e32 v42, v42, v212
	v_mul_f32_e32 v43, v43, v212
	v_mul_f32_e32 v44, v44, v212
	v_mul_f32_e32 v45, v45, v212
	v_mul_f32_e32 v42, v42, v48
	v_mul_f32_e32 v43, v43, v49
	v_mul_f32_e32 v44, v44, v50
	v_mul_f32_e32 v45, v45, v51
	v_add_u32_e32 v46, v198, v194
	ds_write_b128 v46, v[42:45]
	v_mov_b32_e32 v43, 1.0
	s_and_b64 vcc, exec, s[6:7]
	v_mov_b32_e32 v47, 1.0
	v_mov_b32_e32 v46, 1.0
	v_mov_b32_e32 v45, 1.0
	v_mov_b32_e32 v44, 1.0
	s_cbranch_vccnz .LBB0_933
	global_load_dwordx4 v[44:47], v[150:151], off offset:128
	s_waitcnt vmcnt(0)
.LBB0_933:
	v_mul_f32_e32 v38, v38, v212
	v_mul_f32_e32 v39, v39, v212
	v_mul_f32_e32 v40, v40, v212
	v_mul_f32_e32 v41, v41, v212
	v_mul_f32_e32 v38, v38, v44
	v_mul_f32_e32 v39, v39, v45
	v_mul_f32_e32 v40, v40, v46
	v_mul_f32_e32 v41, v41, v47
	v_add_u32_e32 v42, v198, v195
	ds_write_b128 v42, v[38:41]
	s_and_b64 vcc, exec, s[6:7]
	v_mov_b32_e32 v42, 1.0
	v_mov_b32_e32 v41, 1.0
	v_mov_b32_e32 v40, 1.0
	s_cbranch_vccnz .LBB0_935
	global_load_dwordx4 v[40:43], v[150:151], off offset:192
	s_waitcnt vmcnt(0)
.LBB0_935:
	v_mul_f32_e32 v34, v34, v212
	v_mul_f32_e32 v35, v35, v212
	v_mul_f32_e32 v36, v36, v212
	v_mul_f32_e32 v37, v37, v212
	v_mul_f32_e32 v34, v34, v40
	v_mul_f32_e32 v35, v35, v41
	v_mul_f32_e32 v36, v36, v42
	v_mul_f32_e32 v37, v37, v43
	v_add_u32_e32 v38, v198, v196
	ds_write_b128 v38, v[34:37]
	v_mov_b32_e32 v35, 1.0
	s_and_b64 vcc, exec, s[6:7]
	v_mov_b32_e32 v39, 1.0
	v_mov_b32_e32 v38, 1.0
	v_mov_b32_e32 v37, 1.0
	v_mov_b32_e32 v36, 1.0
	s_cbranch_vccnz .LBB0_937
	global_load_dwordx4 v[36:39], v[150:151], off
	s_waitcnt vmcnt(0)
.LBB0_937:
	v_mul_f32_e32 v30, v30, v211
	v_mul_f32_e32 v31, v31, v211
	v_mul_f32_e32 v32, v32, v211
	v_mul_f32_e32 v33, v33, v211
	v_mul_f32_e32 v30, v30, v36
	v_mul_f32_e32 v31, v31, v37
	v_mul_f32_e32 v32, v32, v38
	v_mul_f32_e32 v33, v33, v39
	v_add_u32_e32 v34, v199, v192
	ds_write_b128 v34, v[30:33]
	s_and_b64 vcc, exec, s[6:7]
	v_mov_b32_e32 v34, 1.0
	v_mov_b32_e32 v33, 1.0
	v_mov_b32_e32 v32, 1.0
	s_cbranch_vccnz .LBB0_939
	global_load_dwordx4 v[32:35], v[150:151], off offset:64
	s_waitcnt vmcnt(0)
.LBB0_939:
	v_mul_f32_e32 v26, v26, v211
	v_mul_f32_e32 v27, v27, v211
	v_mul_f32_e32 v28, v28, v211
	v_mul_f32_e32 v29, v29, v211
	v_mul_f32_e32 v26, v26, v32
	v_mul_f32_e32 v27, v27, v33
	v_mul_f32_e32 v28, v28, v34
	v_mul_f32_e32 v29, v29, v35
	v_add_u32_e32 v30, v199, v194
	ds_write_b128 v30, v[26:29]
	v_mov_b32_e32 v27, 1.0
	s_and_b64 vcc, exec, s[6:7]
	v_mov_b32_e32 v31, 1.0
	v_mov_b32_e32 v30, 1.0
	v_mov_b32_e32 v29, 1.0
	v_mov_b32_e32 v28, 1.0
	s_cbranch_vccnz .LBB0_941
	global_load_dwordx4 v[28:31], v[150:151], off offset:128
	s_waitcnt vmcnt(0)
.LBB0_941:
	v_mul_f32_e32 v22, v22, v211
	v_mul_f32_e32 v23, v23, v211
	v_mul_f32_e32 v24, v24, v211
	v_mul_f32_e32 v25, v25, v211
	v_mul_f32_e32 v22, v22, v28
	v_mul_f32_e32 v23, v23, v29
	v_mul_f32_e32 v24, v24, v30
	v_mul_f32_e32 v25, v25, v31
	v_add_u32_e32 v26, v199, v195
	ds_write_b128 v26, v[22:25]
	s_and_b64 vcc, exec, s[6:7]
	v_mov_b32_e32 v26, 1.0
	v_mov_b32_e32 v25, 1.0
	v_mov_b32_e32 v24, 1.0
	s_cbranch_vccnz .LBB0_943
	global_load_dwordx4 v[24:27], v[150:151], off offset:192
	s_waitcnt vmcnt(0)
.LBB0_943:
	v_mul_f32_e32 v18, v18, v211
	v_mul_f32_e32 v19, v19, v211
	v_mul_f32_e32 v20, v20, v211
	v_mul_f32_e32 v21, v21, v211
	v_mul_f32_e32 v18, v18, v24
	v_mul_f32_e32 v19, v19, v25
	v_mul_f32_e32 v20, v20, v26
	v_mul_f32_e32 v21, v21, v27
	v_add_u32_e32 v22, v199, v196
	ds_write_b128 v22, v[18:21]
	v_mov_b32_e32 v19, 1.0
	s_and_b64 vcc, exec, s[6:7]
	v_mov_b32_e32 v23, 1.0
	v_mov_b32_e32 v22, 1.0
	v_mov_b32_e32 v21, 1.0
	v_mov_b32_e32 v20, 1.0
	s_cbranch_vccnz .LBB0_945
	global_load_dwordx4 v[20:23], v[150:151], off
	s_waitcnt vmcnt(0)
.LBB0_945:
	v_mul_f32_e32 v14, v14, v210
	v_mul_f32_e32 v15, v15, v210
	v_mul_f32_e32 v16, v16, v210
	v_mul_f32_e32 v17, v17, v210
	v_mul_f32_e32 v14, v14, v20
	v_mul_f32_e32 v15, v15, v21
	v_mul_f32_e32 v16, v16, v22
	v_mul_f32_e32 v17, v17, v23
	v_add_u32_e32 v18, v200, v192
	ds_write_b128 v18, v[14:17]
	s_and_b64 vcc, exec, s[6:7]
	v_mov_b32_e32 v18, 1.0
	v_mov_b32_e32 v17, 1.0
	v_mov_b32_e32 v16, 1.0
	s_cbranch_vccnz .LBB0_947
	global_load_dwordx4 v[16:19], v[150:151], off offset:64
	s_waitcnt vmcnt(0)
.LBB0_947:
	v_mul_f32_e32 v10, v10, v210
	v_mul_f32_e32 v11, v11, v210
	v_mul_f32_e32 v12, v12, v210
	v_mul_f32_e32 v13, v13, v210
	v_mul_f32_e32 v10, v10, v16
	v_mul_f32_e32 v11, v11, v17
	v_mul_f32_e32 v12, v12, v18
	v_mul_f32_e32 v13, v13, v19
	v_add_u32_e32 v14, v200, v194
	ds_write_b128 v14, v[10:13]
	v_mov_b32_e32 v11, 1.0
	s_and_b64 vcc, exec, s[6:7]
	v_mov_b32_e32 v15, 1.0
	v_mov_b32_e32 v14, 1.0
	v_mov_b32_e32 v13, 1.0
	v_mov_b32_e32 v12, 1.0
	s_cbranch_vccnz .LBB0_949
	global_load_dwordx4 v[12:15], v[150:151], off offset:128
	s_waitcnt vmcnt(0)
.LBB0_949:
	v_mul_f32_e32 v6, v6, v210
	v_mul_f32_e32 v7, v7, v210
	v_mul_f32_e32 v8, v8, v210
	v_mul_f32_e32 v9, v9, v210
	v_mul_f32_e32 v6, v6, v12
	v_mul_f32_e32 v7, v7, v13
	v_mul_f32_e32 v8, v8, v14
	v_mul_f32_e32 v9, v9, v15
	v_add_u32_e32 v10, v200, v195
	ds_write_b128 v10, v[6:9]
	s_and_b64 vcc, exec, s[6:7]
	v_mov_b32_e32 v10, 1.0
	v_mov_b32_e32 v9, 1.0
	v_mov_b32_e32 v8, 1.0
	s_cbranch_vccnz .LBB0_951
	global_load_dwordx4 v[8:11], v[150:151], off offset:192
	s_waitcnt vmcnt(0)
.LBB0_951:
	v_mul_f32_e32 v2, v2, v210
	v_mul_f32_e32 v3, v3, v210
	v_mul_f32_e32 v4, v4, v210
	v_mul_f32_e32 v5, v5, v210
	v_mul_f32_e32 v2, v2, v8
	v_mul_f32_e32 v3, v3, v9
	v_mul_f32_e32 v4, v4, v10
	v_mul_f32_e32 v5, v5, v11
	v_add_u32_e32 v6, v200, v196
	ds_write_b128 v6, v[2:5]

.LBB0_965:
	s_or_b64 exec, exec, s[8:9]
	s_sub_i32 s3, 7, s90
	s_mul_i32 s3, s33, s3
	v_mov_b32_e32 v1, 0

.LBB0_1107:
	s_or_b64 exec, exec, s[6:7]
	s_sub_i32 s4, 8, s90
	s_mul_i32 s33, s33, s4
	v_mov_b32_e32 v1, 0
